# LN2 forget-gate dot products: straight-line with two half-batches of weight loads in flight (was 16 serialized L2 round trips per row)
# baseline (speedup 1.0000x reference)
.LBB0_1143:
	s_waitcnt vmcnt(0)
	v_mov_b32_e32 v0, 0
	v_mov_b32_e32 v1, v0
	v_mov_b32_e32 v80, v0
	v_mov_b32_e32 v81, v0
	v_mov_b32_e32 v74, v0
	v_mov_b32_e32 v75, v0
	v_mov_b32_e32 v72, v0
	v_mov_b32_e32 v73, v0
	v_mov_b32_e32 v70, v0
	v_mov_b32_e32 v71, v0
	v_mov_b32_e32 v68, v0
	v_mov_b32_e32 v69, v0
	v_mov_b32_e32 v66, v0
	v_mov_b32_e32 v67, v0
	v_mov_b32_e32 v2, v0
	v_mov_b32_e32 v3, v0
	v_mul_u32_u24_e32 v134, 0x2040, v28
	v_add_u32_e32 v134, 0x2000, v134
	global_load_dwordx2 v[130:131], v[58:59], off offset:-4
	global_load_dwordx2 v[132:133], v[56:57], off offset:-4
	s_mov_b64 s[10:11], s[16:17]
	global_load_dwordx4 v[204:207], v134, s[10:11]
	global_load_dwordx4 v[208:211], v134, s[10:11] offset:16
	global_load_dwordx4 v[212:215], v134, s[10:11] offset:32
	global_load_dwordx4 v[216:219], v134, s[10:11] offset:48
	s_add_u32 s10, s16, 0x2040
	s_addc_u32 s11, s17, 0
	global_load_dwordx4 v[220:223], v134, s[10:11]
	global_load_dwordx4 v[224:227], v134, s[10:11] offset:16
	global_load_dwordx4 v[228:231], v134, s[10:11] offset:32
	global_load_dwordx4 v[232:235], v134, s[10:11] offset:48
	s_add_u32 s10, s16, 0x4080
	s_addc_u32 s11, s17, 0
	global_load_dwordx4 v[236:239], v134, s[10:11]
	global_load_dwordx4 v[240:243], v134, s[10:11] offset:16
	global_load_dwordx4 v[244:247], v134, s[10:11] offset:32
	global_load_dwordx4 v[248:251], v134, s[10:11] offset:48
	s_add_u32 s10, s16, 0x60c0
	s_addc_u32 s11, s17, 0
	global_load_dwordx4 v[114:117], v134, s[10:11]
	global_load_dwordx4 v[118:121], v134, s[10:11] offset:16
	global_load_dwordx4 v[122:125], v134, s[10:11] offset:32
	global_load_dwordx4 v[126:129], v134, s[10:11] offset:48
	s_waitcnt vmcnt(8)
	v_lshlrev_b32_e32 v180, 16, v130
	v_lshlrev_b32_e32 v181, 16, v132
	v_and_b32_e32 v182, 0xffff0000, v130
	v_and_b32_e32 v183, 0xffff0000, v132
	v_add_f32_e32 v174, v180, v181
	v_add_f32_e32 v176, v182, v183
	v_pk_fma_f32 v[80:81], v[204:205], v[174:175], v[80:81] op_sel_hi:[1,0,1]
	v_pk_fma_f32 v[74:75], v[206:207], v[174:175], v[74:75] op_sel_hi:[1,0,1]
	v_pk_fma_f32 v[72:73], v[208:209], v[174:175], v[72:73] op_sel_hi:[1,0,1]
	v_pk_fma_f32 v[70:71], v[210:211], v[174:175], v[70:71] op_sel_hi:[1,0,1]
	v_pk_fma_f32 v[68:69], v[212:213], v[174:175], v[68:69] op_sel_hi:[1,0,1]
	v_pk_fma_f32 v[66:67], v[214:215], v[174:175], v[66:67] op_sel_hi:[1,0,1]
	v_pk_fma_f32 v[2:3], v[216:217], v[174:175], v[2:3] op_sel_hi:[1,0,1]
	v_pk_fma_f32 v[0:1], v[218:219], v[174:175], v[0:1] op_sel_hi:[1,0,1]
	v_pk_fma_f32 v[80:81], v[220:221], v[176:177], v[80:81] op_sel_hi:[1,0,1]
	v_pk_fma_f32 v[74:75], v[222:223], v[176:177], v[74:75] op_sel_hi:[1,0,1]
	v_pk_fma_f32 v[72:73], v[224:225], v[176:177], v[72:73] op_sel_hi:[1,0,1]
	v_pk_fma_f32 v[70:71], v[226:227], v[176:177], v[70:71] op_sel_hi:[1,0,1]
	v_pk_fma_f32 v[68:69], v[228:229], v[176:177], v[68:69] op_sel_hi:[1,0,1]
	v_pk_fma_f32 v[66:67], v[230:231], v[176:177], v[66:67] op_sel_hi:[1,0,1]
	v_pk_fma_f32 v[2:3], v[232:233], v[176:177], v[2:3] op_sel_hi:[1,0,1]
	v_pk_fma_f32 v[0:1], v[234:235], v[176:177], v[0:1] op_sel_hi:[1,0,1]
	global_load_dwordx2 v[136:137], v[58:59], off offset:508
	global_load_dwordx2 v[138:139], v[56:57], off offset:508
	s_add_u32 s10, s16, 0x204000
	s_addc_u32 s11, s17, 0
	global_load_dwordx4 v[204:207], v134, s[10:11]
	global_load_dwordx4 v[208:211], v134, s[10:11] offset:16
	global_load_dwordx4 v[212:215], v134, s[10:11] offset:32
	global_load_dwordx4 v[216:219], v134, s[10:11] offset:48
	s_add_u32 s10, s16, 0x206040
	s_addc_u32 s11, s17, 0
	global_load_dwordx4 v[220:223], v134, s[10:11]
	global_load_dwordx4 v[224:227], v134, s[10:11] offset:16
	global_load_dwordx4 v[228:231], v134, s[10:11] offset:32
	global_load_dwordx4 v[232:235], v134, s[10:11] offset:48
	s_waitcnt vmcnt(10)
	v_lshlrev_b32_e32 v180, 16, v131
	v_lshlrev_b32_e32 v181, 16, v133
	v_and_b32_e32 v182, 0xffff0000, v131
	v_and_b32_e32 v183, 0xffff0000, v133
	v_add_f32_e32 v174, v180, v181
	v_add_f32_e32 v176, v182, v183
	v_pk_fma_f32 v[80:81], v[236:237], v[174:175], v[80:81] op_sel_hi:[1,0,1]
	v_pk_fma_f32 v[74:75], v[238:239], v[174:175], v[74:75] op_sel_hi:[1,0,1]
	v_pk_fma_f32 v[72:73], v[240:241], v[174:175], v[72:73] op_sel_hi:[1,0,1]
	v_pk_fma_f32 v[70:71], v[242:243], v[174:175], v[70:71] op_sel_hi:[1,0,1]
	v_pk_fma_f32 v[68:69], v[244:245], v[174:175], v[68:69] op_sel_hi:[1,0,1]
	v_pk_fma_f32 v[66:67], v[246:247], v[174:175], v[66:67] op_sel_hi:[1,0,1]
	v_pk_fma_f32 v[2:3], v[248:249], v[174:175], v[2:3] op_sel_hi:[1,0,1]
	v_pk_fma_f32 v[0:1], v[250:251], v[174:175], v[0:1] op_sel_hi:[1,0,1]
	v_pk_fma_f32 v[80:81], v[114:115], v[176:177], v[80:81] op_sel_hi:[1,0,1]
	v_pk_fma_f32 v[74:75], v[116:117], v[176:177], v[74:75] op_sel_hi:[1,0,1]
	v_pk_fma_f32 v[72:73], v[118:119], v[176:177], v[72:73] op_sel_hi:[1,0,1]
	v_pk_fma_f32 v[70:71], v[120:121], v[176:177], v[70:71] op_sel_hi:[1,0,1]
	v_pk_fma_f32 v[68:69], v[122:123], v[176:177], v[68:69] op_sel_hi:[1,0,1]
	v_pk_fma_f32 v[66:67], v[124:125], v[176:177], v[66:67] op_sel_hi:[1,0,1]
	v_pk_fma_f32 v[2:3], v[126:127], v[176:177], v[2:3] op_sel_hi:[1,0,1]
	v_pk_fma_f32 v[0:1], v[128:129], v[176:177], v[0:1] op_sel_hi:[1,0,1]
	s_add_u32 s10, s16, 0x208080
	s_addc_u32 s11, s17, 0
	global_load_dwordx4 v[236:239], v134, s[10:11]
	global_load_dwordx4 v[240:243], v134, s[10:11] offset:16
	global_load_dwordx4 v[244:247], v134, s[10:11] offset:32
	global_load_dwordx4 v[248:251], v134, s[10:11] offset:48
	s_add_u32 s10, s16, 0x20a0c0
	s_addc_u32 s11, s17, 0
	global_load_dwordx4 v[114:117], v134, s[10:11]
	global_load_dwordx4 v[118:121], v134, s[10:11] offset:16
	global_load_dwordx4 v[122:125], v134, s[10:11] offset:32
	global_load_dwordx4 v[126:129], v134, s[10:11] offset:48
	s_waitcnt vmcnt(8)
	v_lshlrev_b32_e32 v180, 16, v136
	v_lshlrev_b32_e32 v181, 16, v138
	v_and_b32_e32 v182, 0xffff0000, v136
	v_and_b32_e32 v183, 0xffff0000, v138
	v_add_f32_e32 v174, v180, v181
	v_add_f32_e32 v176, v182, v183
	v_pk_fma_f32 v[80:81], v[204:205], v[174:175], v[80:81] op_sel_hi:[1,0,1]
	v_pk_fma_f32 v[74:75], v[206:207], v[174:175], v[74:75] op_sel_hi:[1,0,1]
	v_pk_fma_f32 v[72:73], v[208:209], v[174:175], v[72:73] op_sel_hi:[1,0,1]
	v_pk_fma_f32 v[70:71], v[210:211], v[174:175], v[70:71] op_sel_hi:[1,0,1]
	v_pk_fma_f32 v[68:69], v[212:213], v[174:175], v[68:69] op_sel_hi:[1,0,1]
	v_pk_fma_f32 v[66:67], v[214:215], v[174:175], v[66:67] op_sel_hi:[1,0,1]
	v_pk_fma_f32 v[2:3], v[216:217], v[174:175], v[2:3] op_sel_hi:[1,0,1]
	v_pk_fma_f32 v[0:1], v[218:219], v[174:175], v[0:1] op_sel_hi:[1,0,1]
	v_pk_fma_f32 v[80:81], v[220:221], v[176:177], v[80:81] op_sel_hi:[1,0,1]
	v_pk_fma_f32 v[74:75], v[222:223], v[176:177], v[74:75] op_sel_hi:[1,0,1]
	v_pk_fma_f32 v[72:73], v[224:225], v[176:177], v[72:73] op_sel_hi:[1,0,1]
	v_pk_fma_f32 v[70:71], v[226:227], v[176:177], v[70:71] op_sel_hi:[1,0,1]
	v_pk_fma_f32 v[68:69], v[228:229], v[176:177], v[68:69] op_sel_hi:[1,0,1]
	v_pk_fma_f32 v[66:67], v[230:231], v[176:177], v[66:67] op_sel_hi:[1,0,1]
	v_pk_fma_f32 v[2:3], v[232:233], v[176:177], v[2:3] op_sel_hi:[1,0,1]
	v_pk_fma_f32 v[0:1], v[234:235], v[176:177], v[0:1] op_sel_hi:[1,0,1]
	global_load_dwordx2 v[130:131], v[58:59], off offset:1020
	global_load_dwordx2 v[132:133], v[56:57], off offset:1020
	s_add_u32 s10, s16, 0x408000
	s_addc_u32 s11, s17, 0
	global_load_dwordx4 v[204:207], v134, s[10:11]
	global_load_dwordx4 v[208:211], v134, s[10:11] offset:16
	global_load_dwordx4 v[212:215], v134, s[10:11] offset:32
	global_load_dwordx4 v[216:219], v134, s[10:11] offset:48
	s_add_u32 s10, s16, 0x40a040
	s_addc_u32 s11, s17, 0
	global_load_dwordx4 v[220:223], v134, s[10:11]
	global_load_dwordx4 v[224:227], v134, s[10:11] offset:16
	global_load_dwordx4 v[228:231], v134, s[10:11] offset:32
	global_load_dwordx4 v[232:235], v134, s[10:11] offset:48
	s_waitcnt vmcnt(10)
	v_lshlrev_b32_e32 v180, 16, v137
	v_lshlrev_b32_e32 v181, 16, v139
	v_and_b32_e32 v182, 0xffff0000, v137
	v_and_b32_e32 v183, 0xffff0000, v139
	v_add_f32_e32 v174, v180, v181
	v_add_f32_e32 v176, v182, v183
	v_pk_fma_f32 v[80:81], v[236:237], v[174:175], v[80:81] op_sel_hi:[1,0,1]
	v_pk_fma_f32 v[74:75], v[238:239], v[174:175], v[74:75] op_sel_hi:[1,0,1]
	v_pk_fma_f32 v[72:73], v[240:241], v[174:175], v[72:73] op_sel_hi:[1,0,1]
	v_pk_fma_f32 v[70:71], v[242:243], v[174:175], v[70:71] op_sel_hi:[1,0,1]
	v_pk_fma_f32 v[68:69], v[244:245], v[174:175], v[68:69] op_sel_hi:[1,0,1]
	v_pk_fma_f32 v[66:67], v[246:247], v[174:175], v[66:67] op_sel_hi:[1,0,1]
	v_pk_fma_f32 v[2:3], v[248:249], v[174:175], v[2:3] op_sel_hi:[1,0,1]
	v_pk_fma_f32 v[0:1], v[250:251], v[174:175], v[0:1] op_sel_hi:[1,0,1]
	v_pk_fma_f32 v[80:81], v[114:115], v[176:177], v[80:81] op_sel_hi:[1,0,1]
	v_pk_fma_f32 v[74:75], v[116:117], v[176:177], v[74:75] op_sel_hi:[1,0,1]
	v_pk_fma_f32 v[72:73], v[118:119], v[176:177], v[72:73] op_sel_hi:[1,0,1]
	v_pk_fma_f32 v[70:71], v[120:121], v[176:177], v[70:71] op_sel_hi:[1,0,1]
	v_pk_fma_f32 v[68:69], v[122:123], v[176:177], v[68:69] op_sel_hi:[1,0,1]
	v_pk_fma_f32 v[66:67], v[124:125], v[176:177], v[66:67] op_sel_hi:[1,0,1]
	v_pk_fma_f32 v[2:3], v[126:127], v[176:177], v[2:3] op_sel_hi:[1,0,1]
	v_pk_fma_f32 v[0:1], v[128:129], v[176:177], v[0:1] op_sel_hi:[1,0,1]
	s_add_u32 s10, s16, 0x40c080
	s_addc_u32 s11, s17, 0
	global_load_dwordx4 v[236:239], v134, s[10:11]
	global_load_dwordx4 v[240:243], v134, s[10:11] offset:16
	global_load_dwordx4 v[244:247], v134, s[10:11] offset:32
	global_load_dwordx4 v[248:251], v134, s[10:11] offset:48
	s_add_u32 s10, s16, 0x40e0c0
	s_addc_u32 s11, s17, 0
	global_load_dwordx4 v[114:117], v134, s[10:11]
	global_load_dwordx4 v[118:121], v134, s[10:11] offset:16
	global_load_dwordx4 v[122:125], v134, s[10:11] offset:32
	global_load_dwordx4 v[126:129], v134, s[10:11] offset:48
	s_waitcnt vmcnt(8)
	v_lshlrev_b32_e32 v180, 16, v130
	v_lshlrev_b32_e32 v181, 16, v132
	v_and_b32_e32 v182, 0xffff0000, v130
	v_and_b32_e32 v183, 0xffff0000, v132
	v_add_f32_e32 v174, v180, v181
	v_add_f32_e32 v176, v182, v183
	v_pk_fma_f32 v[80:81], v[204:205], v[174:175], v[80:81] op_sel_hi:[1,0,1]
	v_pk_fma_f32 v[74:75], v[206:207], v[174:175], v[74:75] op_sel_hi:[1,0,1]
	v_pk_fma_f32 v[72:73], v[208:209], v[174:175], v[72:73] op_sel_hi:[1,0,1]
	v_pk_fma_f32 v[70:71], v[210:211], v[174:175], v[70:71] op_sel_hi:[1,0,1]
	v_pk_fma_f32 v[68:69], v[212:213], v[174:175], v[68:69] op_sel_hi:[1,0,1]
	v_pk_fma_f32 v[66:67], v[214:215], v[174:175], v[66:67] op_sel_hi:[1,0,1]
	v_pk_fma_f32 v[2:3], v[216:217], v[174:175], v[2:3] op_sel_hi:[1,0,1]
	v_pk_fma_f32 v[0:1], v[218:219], v[174:175], v[0:1] op_sel_hi:[1,0,1]
	v_pk_fma_f32 v[80:81], v[220:221], v[176:177], v[80:81] op_sel_hi:[1,0,1]
	v_pk_fma_f32 v[74:75], v[222:223], v[176:177], v[74:75] op_sel_hi:[1,0,1]
	v_pk_fma_f32 v[72:73], v[224:225], v[176:177], v[72:73] op_sel_hi:[1,0,1]
	v_pk_fma_f32 v[70:71], v[226:227], v[176:177], v[70:71] op_sel_hi:[1,0,1]
	v_pk_fma_f32 v[68:69], v[228:229], v[176:177], v[68:69] op_sel_hi:[1,0,1]
	v_pk_fma_f32 v[66:67], v[230:231], v[176:177], v[66:67] op_sel_hi:[1,0,1]
	v_pk_fma_f32 v[2:3], v[232:233], v[176:177], v[2:3] op_sel_hi:[1,0,1]
	v_pk_fma_f32 v[0:1], v[234:235], v[176:177], v[0:1] op_sel_hi:[1,0,1]
	global_load_dwordx2 v[136:137], v[58:59], off offset:1532
	global_load_dwordx2 v[138:139], v[56:57], off offset:1532
	s_add_u32 s10, s16, 0x60c000
	s_addc_u32 s11, s17, 0
	global_load_dwordx4 v[204:207], v134, s[10:11]
	global_load_dwordx4 v[208:211], v134, s[10:11] offset:16
	global_load_dwordx4 v[212:215], v134, s[10:11] offset:32
	global_load_dwordx4 v[216:219], v134, s[10:11] offset:48
	s_add_u32 s10, s16, 0x60e040
	s_addc_u32 s11, s17, 0
	global_load_dwordx4 v[220:223], v134, s[10:11]
	global_load_dwordx4 v[224:227], v134, s[10:11] offset:16
	global_load_dwordx4 v[228:231], v134, s[10:11] offset:32
	global_load_dwordx4 v[232:235], v134, s[10:11] offset:48
	s_waitcnt vmcnt(10)
	v_lshlrev_b32_e32 v180, 16, v131
	v_lshlrev_b32_e32 v181, 16, v133
	v_and_b32_e32 v182, 0xffff0000, v131
	v_and_b32_e32 v183, 0xffff0000, v133
	v_add_f32_e32 v174, v180, v181
	v_add_f32_e32 v176, v182, v183
	v_pk_fma_f32 v[80:81], v[236:237], v[174:175], v[80:81] op_sel_hi:[1,0,1]
	v_pk_fma_f32 v[74:75], v[238:239], v[174:175], v[74:75] op_sel_hi:[1,0,1]
	v_pk_fma_f32 v[72:73], v[240:241], v[174:175], v[72:73] op_sel_hi:[1,0,1]
	v_pk_fma_f32 v[70:71], v[242:243], v[174:175], v[70:71] op_sel_hi:[1,0,1]
	v_pk_fma_f32 v[68:69], v[244:245], v[174:175], v[68:69] op_sel_hi:[1,0,1]
	v_pk_fma_f32 v[66:67], v[246:247], v[174:175], v[66:67] op_sel_hi:[1,0,1]
	v_pk_fma_f32 v[2:3], v[248:249], v[174:175], v[2:3] op_sel_hi:[1,0,1]
	v_pk_fma_f32 v[0:1], v[250:251], v[174:175], v[0:1] op_sel_hi:[1,0,1]
	v_pk_fma_f32 v[80:81], v[114:115], v[176:177], v[80:81] op_sel_hi:[1,0,1]
	v_pk_fma_f32 v[74:75], v[116:117], v[176:177], v[74:75] op_sel_hi:[1,0,1]
	v_pk_fma_f32 v[72:73], v[118:119], v[176:177], v[72:73] op_sel_hi:[1,0,1]
	v_pk_fma_f32 v[70:71], v[120:121], v[176:177], v[70:71] op_sel_hi:[1,0,1]
	v_pk_fma_f32 v[68:69], v[122:123], v[176:177], v[68:69] op_sel_hi:[1,0,1]
	v_pk_fma_f32 v[66:67], v[124:125], v[176:177], v[66:67] op_sel_hi:[1,0,1]
	v_pk_fma_f32 v[2:3], v[126:127], v[176:177], v[2:3] op_sel_hi:[1,0,1]
	v_pk_fma_f32 v[0:1], v[128:129], v[176:177], v[0:1] op_sel_hi:[1,0,1]
	s_add_u32 s10, s16, 0x610080
	s_addc_u32 s11, s17, 0
	global_load_dwordx4 v[236:239], v134, s[10:11]
	global_load_dwordx4 v[240:243], v134, s[10:11] offset:16
	global_load_dwordx4 v[244:247], v134, s[10:11] offset:32
	global_load_dwordx4 v[248:251], v134, s[10:11] offset:48
	s_add_u32 s10, s16, 0x6120c0
	s_addc_u32 s11, s17, 0
	global_load_dwordx4 v[114:117], v134, s[10:11]
	global_load_dwordx4 v[118:121], v134, s[10:11] offset:16
	global_load_dwordx4 v[122:125], v134, s[10:11] offset:32
	global_load_dwordx4 v[126:129], v134, s[10:11] offset:48
	s_waitcnt vmcnt(8)
	v_lshlrev_b32_e32 v180, 16, v136
	v_lshlrev_b32_e32 v181, 16, v138
	v_and_b32_e32 v182, 0xffff0000, v136
	v_and_b32_e32 v183, 0xffff0000, v138
	v_add_f32_e32 v174, v180, v181
	v_add_f32_e32 v176, v182, v183
	v_pk_fma_f32 v[80:81], v[204:205], v[174:175], v[80:81] op_sel_hi:[1,0,1]
	v_pk_fma_f32 v[74:75], v[206:207], v[174:175], v[74:75] op_sel_hi:[1,0,1]
	v_pk_fma_f32 v[72:73], v[208:209], v[174:175], v[72:73] op_sel_hi:[1,0,1]
	v_pk_fma_f32 v[70:71], v[210:211], v[174:175], v[70:71] op_sel_hi:[1,0,1]
	v_pk_fma_f32 v[68:69], v[212:213], v[174:175], v[68:69] op_sel_hi:[1,0,1]
	v_pk_fma_f32 v[66:67], v[214:215], v[174:175], v[66:67] op_sel_hi:[1,0,1]
	v_pk_fma_f32 v[2:3], v[216:217], v[174:175], v[2:3] op_sel_hi:[1,0,1]
	v_pk_fma_f32 v[0:1], v[218:219], v[174:175], v[0:1] op_sel_hi:[1,0,1]
	v_pk_fma_f32 v[80:81], v[220:221], v[176:177], v[80:81] op_sel_hi:[1,0,1]
	v_pk_fma_f32 v[74:75], v[222:223], v[176:177], v[74:75] op_sel_hi:[1,0,1]
	v_pk_fma_f32 v[72:73], v[224:225], v[176:177], v[72:73] op_sel_hi:[1,0,1]
	v_pk_fma_f32 v[70:71], v[226:227], v[176:177], v[70:71] op_sel_hi:[1,0,1]
	v_pk_fma_f32 v[68:69], v[228:229], v[176:177], v[68:69] op_sel_hi:[1,0,1]
	v_pk_fma_f32 v[66:67], v[230:231], v[176:177], v[66:67] op_sel_hi:[1,0,1]
	v_pk_fma_f32 v[2:3], v[232:233], v[176:177], v[2:3] op_sel_hi:[1,0,1]
	v_pk_fma_f32 v[0:1], v[234:235], v[176:177], v[0:1] op_sel_hi:[1,0,1]
	s_waitcnt vmcnt(0)
	v_lshlrev_b32_e32 v180, 16, v137
	v_lshlrev_b32_e32 v181, 16, v139
	v_and_b32_e32 v182, 0xffff0000, v137
	v_and_b32_e32 v183, 0xffff0000, v139
	v_add_f32_e32 v174, v180, v181
	v_add_f32_e32 v176, v182, v183
	v_pk_fma_f32 v[80:81], v[236:237], v[174:175], v[80:81] op_sel_hi:[1,0,1]
	v_pk_fma_f32 v[74:75], v[238:239], v[174:175], v[74:75] op_sel_hi:[1,0,1]
	v_pk_fma_f32 v[72:73], v[240:241], v[174:175], v[72:73] op_sel_hi:[1,0,1]
	v_pk_fma_f32 v[70:71], v[242:243], v[174:175], v[70:71] op_sel_hi:[1,0,1]
	v_pk_fma_f32 v[68:69], v[244:245], v[174:175], v[68:69] op_sel_hi:[1,0,1]
	v_pk_fma_f32 v[66:67], v[246:247], v[174:175], v[66:67] op_sel_hi:[1,0,1]
	v_pk_fma_f32 v[2:3], v[248:249], v[174:175], v[2:3] op_sel_hi:[1,0,1]
	v_pk_fma_f32 v[0:1], v[250:251], v[174:175], v[0:1] op_sel_hi:[1,0,1]
	v_pk_fma_f32 v[80:81], v[114:115], v[176:177], v[80:81] op_sel_hi:[1,0,1]
	v_pk_fma_f32 v[74:75], v[116:117], v[176:177], v[74:75] op_sel_hi:[1,0,1]
	v_pk_fma_f32 v[72:73], v[118:119], v[176:177], v[72:73] op_sel_hi:[1,0,1]
	v_pk_fma_f32 v[70:71], v[120:121], v[176:177], v[70:71] op_sel_hi:[1,0,1]
	v_pk_fma_f32 v[68:69], v[122:123], v[176:177], v[68:69] op_sel_hi:[1,0,1]
	v_pk_fma_f32 v[66:67], v[124:125], v[176:177], v[66:67] op_sel_hi:[1,0,1]
	v_pk_fma_f32 v[2:3], v[126:127], v[176:177], v[2:3] op_sel_hi:[1,0,1]
	v_pk_fma_f32 v[0:1], v[128:129], v[176:177], v[0:1] op_sel_hi:[1,0,1]
	s_mov_b64 s[8:9], exec
	v_and_b32_e32 v109, 60, v28
	global_load_dword v110, v109, s[18:19]
	ds_bpermute_b32 v92, v29, v80
	ds_bpermute_b32 v93, v29, v81
	ds_bpermute_b32 v94, v29, v74
	ds_bpermute_b32 v95, v29, v75
	ds_bpermute_b32 v96, v29, v72
	ds_bpermute_b32 v97, v29, v73
	ds_bpermute_b32 v98, v29, v70
	ds_bpermute_b32 v99, v29, v71
	s_waitcnt lgkmcnt(0)
	ds_bpermute_b32 v100, v29, v68
	ds_bpermute_b32 v101, v29, v69
	ds_bpermute_b32 v102, v29, v66
	ds_bpermute_b32 v103, v29, v67
	ds_bpermute_b32 v104, v29, v2
	ds_bpermute_b32 v105, v29, v3
	ds_bpermute_b32 v106, v29, v0
	ds_bpermute_b32 v107, v29, v1
	v_add_f32_e32 v80, v80, v92
	v_add_f32_e32 v81, v81, v93
	v_add_f32_e32 v74, v74, v94
	v_add_f32_e32 v75, v75, v95
	v_add_f32_e32 v72, v72, v96
	v_add_f32_e32 v73, v73, v97
	v_add_f32_e32 v70, v70, v98
	v_add_f32_e32 v71, v71, v99
	s_waitcnt lgkmcnt(0)
	ds_bpermute_b32 v92, v86, v80
	ds_bpermute_b32 v93, v86, v81
	ds_bpermute_b32 v94, v86, v74
	ds_bpermute_b32 v95, v86, v75
	ds_bpermute_b32 v96, v86, v72
	ds_bpermute_b32 v97, v86, v73
	ds_bpermute_b32 v98, v86, v70
	ds_bpermute_b32 v99, v86, v71
	v_add_f32_e32 v68, v68, v100
	v_add_f32_e32 v69, v69, v101
	v_add_f32_e32 v66, v66, v102
	v_add_f32_e32 v67, v67, v103
	v_add_f32_e32 v2, v2, v104
	v_add_f32_e32 v3, v3, v105
	v_add_f32_e32 v0, v0, v106
	v_add_f32_e32 v1, v1, v107
	s_waitcnt lgkmcnt(0)
	ds_bpermute_b32 v100, v86, v68
	ds_bpermute_b32 v101, v86, v69
	ds_bpermute_b32 v102, v86, v66
	ds_bpermute_b32 v103, v86, v67
	ds_bpermute_b32 v104, v86, v2
	ds_bpermute_b32 v105, v86, v3
	ds_bpermute_b32 v106, v86, v0
	ds_bpermute_b32 v107, v86, v1
	v_add_f32_e32 v80, v80, v92
	v_add_f32_e32 v81, v81, v93
	v_add_f32_e32 v74, v74, v94
	v_add_f32_e32 v75, v75, v95
	v_add_f32_e32 v72, v72, v96
	v_add_f32_e32 v73, v73, v97
	v_add_f32_e32 v70, v70, v98
	v_add_f32_e32 v71, v71, v99
	s_waitcnt lgkmcnt(0)
	ds_bpermute_b32 v92, v87, v80
	ds_bpermute_b32 v93, v87, v81
	ds_bpermute_b32 v94, v87, v74
	ds_bpermute_b32 v95, v87, v75
	ds_bpermute_b32 v96, v87, v72
	ds_bpermute_b32 v97, v87, v73
	ds_bpermute_b32 v98, v87, v70
	ds_bpermute_b32 v99, v87, v71
	v_add_f32_e32 v68, v68, v100
	v_add_f32_e32 v69, v69, v101
	v_add_f32_e32 v66, v66, v102
	v_add_f32_e32 v67, v67, v103
	v_add_f32_e32 v2, v2, v104
	v_add_f32_e32 v3, v3, v105
	v_add_f32_e32 v0, v0, v106
	v_add_f32_e32 v1, v1, v107
	s_waitcnt lgkmcnt(0)
	ds_bpermute_b32 v100, v87, v68
	ds_bpermute_b32 v101, v87, v69
	ds_bpermute_b32 v102, v87, v66
	ds_bpermute_b32 v103, v87, v67
	ds_bpermute_b32 v104, v87, v2
	ds_bpermute_b32 v105, v87, v3
	ds_bpermute_b32 v106, v87, v0
	ds_bpermute_b32 v107, v87, v1
	v_add_f32_e32 v80, v80, v92
	v_add_f32_e32 v81, v81, v93
	v_add_f32_e32 v74, v74, v94
	v_add_f32_e32 v75, v75, v95
	v_add_f32_e32 v72, v72, v96
	v_add_f32_e32 v73, v73, v97
	v_add_f32_e32 v70, v70, v98
	v_add_f32_e32 v71, v71, v99
	s_waitcnt lgkmcnt(0)
	ds_bpermute_b32 v92, v88, v80
	ds_bpermute_b32 v93, v88, v81
	ds_bpermute_b32 v94, v88, v74
	ds_bpermute_b32 v95, v88, v75
	ds_bpermute_b32 v96, v88, v72
	ds_bpermute_b32 v97, v88, v73
	ds_bpermute_b32 v98, v88, v70
	ds_bpermute_b32 v99, v88, v71
	v_add_f32_e32 v68, v68, v100
	v_add_f32_e32 v69, v69, v101
	v_add_f32_e32 v66, v66, v102
	v_add_f32_e32 v67, v67, v103
	v_add_f32_e32 v2, v2, v104
	v_add_f32_e32 v3, v3, v105
	v_add_f32_e32 v0, v0, v106
	v_add_f32_e32 v1, v1, v107
	s_waitcnt lgkmcnt(0)
	ds_bpermute_b32 v100, v88, v68
	ds_bpermute_b32 v101, v88, v69
	ds_bpermute_b32 v102, v88, v66
	ds_bpermute_b32 v103, v88, v67
	ds_bpermute_b32 v104, v88, v2
	ds_bpermute_b32 v105, v88, v3
	ds_bpermute_b32 v106, v88, v0
	ds_bpermute_b32 v107, v88, v1
	v_add_f32_e32 v80, v80, v92
	v_add_f32_e32 v81, v81, v93
	v_add_f32_e32 v74, v74, v94
	v_add_f32_e32 v75, v75, v95
	v_add_f32_e32 v72, v72, v96
	v_add_f32_e32 v73, v73, v97
	v_add_f32_e32 v70, v70, v98
	v_add_f32_e32 v71, v71, v99
	s_waitcnt lgkmcnt(0)
	ds_bpermute_b32 v92, v89, v80
	ds_bpermute_b32 v93, v89, v81
	ds_bpermute_b32 v94, v89, v74
	ds_bpermute_b32 v95, v89, v75
	ds_bpermute_b32 v96, v89, v72
	ds_bpermute_b32 v97, v89, v73
	ds_bpermute_b32 v98, v89, v70
	ds_bpermute_b32 v99, v89, v71
	v_add_f32_e32 v68, v68, v100
	v_add_f32_e32 v69, v69, v101
	v_add_f32_e32 v66, v66, v102
	v_add_f32_e32 v67, v67, v103
	v_add_f32_e32 v2, v2, v104
	v_add_f32_e32 v3, v3, v105
	v_add_f32_e32 v0, v0, v106
	v_add_f32_e32 v1, v1, v107
	s_waitcnt lgkmcnt(0)
	ds_bpermute_b32 v100, v89, v68
	ds_bpermute_b32 v101, v89, v69
	ds_bpermute_b32 v102, v89, v66
	ds_bpermute_b32 v103, v89, v67
	ds_bpermute_b32 v104, v89, v2
	ds_bpermute_b32 v105, v89, v3
	ds_bpermute_b32 v106, v89, v0
	ds_bpermute_b32 v107, v89, v1
	v_add_f32_e32 v80, v80, v92
	v_add_f32_e32 v81, v81, v93
	v_add_f32_e32 v74, v74, v94
	v_add_f32_e32 v75, v75, v95
	v_add_f32_e32 v72, v72, v96
	v_add_f32_e32 v73, v73, v97
	v_add_f32_e32 v70, v70, v98
	v_add_f32_e32 v71, v71, v99
	s_waitcnt lgkmcnt(0)
	ds_bpermute_b32 v92, v90, v80
	ds_bpermute_b32 v93, v90, v81
	ds_bpermute_b32 v94, v90, v74
	ds_bpermute_b32 v95, v90, v75
	ds_bpermute_b32 v96, v90, v72
	ds_bpermute_b32 v97, v90, v73
	ds_bpermute_b32 v98, v90, v70
	ds_bpermute_b32 v99, v90, v71
	v_add_f32_e32 v68, v68, v100
	v_add_f32_e32 v69, v69, v101
	v_add_f32_e32 v66, v66, v102
	v_add_f32_e32 v67, v67, v103
	v_add_f32_e32 v2, v2, v104
	v_add_f32_e32 v3, v3, v105
	v_add_f32_e32 v0, v0, v106
	v_add_f32_e32 v1, v1, v107
	s_waitcnt lgkmcnt(0)
	ds_bpermute_b32 v100, v90, v68
	ds_bpermute_b32 v101, v90, v69
	ds_bpermute_b32 v102, v90, v66
	ds_bpermute_b32 v103, v90, v67
	ds_bpermute_b32 v104, v90, v2
	ds_bpermute_b32 v105, v90, v3
	ds_bpermute_b32 v106, v90, v0
	ds_bpermute_b32 v107, v90, v1
	v_add_f32_e32 v80, v80, v92
	v_add_f32_e32 v81, v81, v93
	v_add_f32_e32 v74, v74, v94
	v_add_f32_e32 v75, v75, v95
	v_add_f32_e32 v72, v72, v96
	v_add_f32_e32 v73, v73, v97
	v_add_f32_e32 v70, v70, v98
	v_add_f32_e32 v71, v71, v99
	s_waitcnt lgkmcnt(0)
	v_add_f32_e32 v68, v68, v100
	v_add_f32_e32 v69, v69, v101
	v_add_f32_e32 v66, v66, v102
	v_add_f32_e32 v67, v67, v103
	v_add_f32_e32 v2, v2, v104
	v_add_f32_e32 v3, v3, v105
	v_add_f32_e32 v0, v0, v106
	v_add_f32_e32 v1, v1, v107
	v_mov_b32_e32 v108, v80
	s_mov_b64 vcc, 2
	s_mov_b64 s[10:11], 4
	v_cndmask_b32_e32 v108, v108, v81, vcc
	s_mov_b64 vcc, 8
	v_cndmask_b32_e64 v108, v108, v74, s[10:11]
	s_mov_b64 s[10:11], 16
	v_cndmask_b32_e32 v108, v108, v75, vcc
	s_mov_b64 vcc, 32
	v_cndmask_b32_e64 v108, v108, v72, s[10:11]
	s_mov_b64 s[10:11], 64
	v_cndmask_b32_e32 v108, v108, v73, vcc
	s_mov_b64 vcc, 128
	v_cndmask_b32_e64 v108, v108, v70, s[10:11]
	s_mov_b64 s[10:11], 256
	v_cndmask_b32_e32 v108, v108, v71, vcc
	s_mov_b64 vcc, 512
	v_cndmask_b32_e64 v108, v108, v68, s[10:11]
	s_mov_b64 s[10:11], 1024
	v_cndmask_b32_e32 v108, v108, v69, vcc
	s_mov_b64 vcc, 2048
	v_cndmask_b32_e64 v108, v108, v66, s[10:11]
	s_mov_b64 s[10:11], 4096
	v_cndmask_b32_e32 v108, v108, v67, vcc
	s_mov_b64 vcc, 8192
	v_cndmask_b32_e64 v108, v108, v2, s[10:11]
	s_mov_b64 s[10:11], 16384
	v_cndmask_b32_e32 v108, v108, v3, vcc
	s_mov_b64 vcc, 32768
	v_cndmask_b32_e64 v108, v108, v0, s[10:11]
	v_cndmask_b32_e32 v108, v108, v1, vcc
	s_waitcnt vmcnt(0)
	v_add_f32_e32 v108, v110, v108
	v_mul_f32_e64 v111, |v108|, s97
	v_exp_f32_e32 v111, v111
	s_nop 0
	v_add_f32_e32 v112, 1.0, v111
	v_log_f32_e32 v112, v112
	v_fmamk_f32 v113, v111, 0xbe800000, v194
	v_fma_f32 v113, -v111, v113, 0.5
	v_fma_f32 v113, -v111, v113, 1.0
	v_mul_f32_e32 v113, v111, v113
	v_mul_f32_e32 v61, 0x3f317217, v112
	v_fma_f32 v61, v112, s76, -v61
	v_fmac_f32_e32 v61, 0x3377d1cf, v112
	v_fmac_f32_e32 v61, 0x3f317217, v112
	v_cmp_ngt_f32_e32 vcc, s90, v111
	v_ashrrev_i32_e32 v79, 31, v78
	v_lshl_add_u64 v[62:63], v[78:79], 2, s[34:35]
	v_cndmask_b32_e32 v61, v113, v61, vcc
	v_mul_hi_i32_i24_e32 v65, 0x20400, v76
	v_mul_i32_i24_e32 v64, 0x20400, v76
	v_max_f32_e32 v108, v108, v108
	v_min_f32_e32 v108, 0, v108
	v_lshl_add_u64 v[62:63], v[62:63], 0, v[64:65]
	v_mul_u32_u24_e32 v64, 0x810, v109
	v_mov_b32_e32 v65, 0
	v_sub_f32_e32 v108, v108, v61
	v_lshl_add_u64 v[62:63], v[62:63], 0, v[64:65]
	s_mov_b64 exec, 0xffff
	global_store_dword v[62:63], v108, off
	s_mov_b64 exec, s[8:9]
	s_branch .LBB0_1110
